# fast X: K reads then QK then V reads; lgkm wait moved to chain end; wait-state fix before ones-MFMA
# speedup vs baseline: 1.0785x; 1.0029x over previous
.Lf_459:
	v_mov_b32_e32 v180, v128
	v_mov_b32_e32 v181, v129
	v_mov_b32_e32 v182, v130
	v_mov_b32_e32 v183, v131
	v_mfma_f32_32x32x16_bf16 v[64:79], v[176:179], v[140:143], v[64:79]
	ds_read_b64_tr_b16 v[128:129], v0 offset:24576
	ds_read_b64_tr_b16 v[130:131], v0 offset:25088
	v_exp_f32_e32 v14, v112
	s_mov_b32 s61, s60
	s_mov_b32 s62, s60
	s_mov_b32 s63, s60
	v_mfma_f32_32x32x16_bf16 v[64:79], v[172:175], v[136:139], v[64:79]
	ds_read_b64_tr_b16 v[172:173], v0 offset:25600
	ds_read_b64_tr_b16 v[174:175], v0 offset:26112
	v_exp_f32_e32 v15, v96
	v_mfma_f32_32x32x16_bf16 v[64:79], v[168:171], v[132:135], v[64:79]
	ds_read_b64_tr_b16 v[168:169], v0 offset:26624
	ds_read_b64_tr_b16 v[170:171], v0 offset:27136
	v_exp_f32_e32 v96, v113
	v_mfma_f32_32x32x16_bf16 v[64:79], v[164:167], v[180:183], v[64:79]
	ds_read_b64_tr_b16 v[164:165], v0 offset:27648
	ds_read_b64_tr_b16 v[166:167], v0 offset:28160
	v_exp_f32_e32 v97, v97
	v_mfma_f32_32x32x16_bf16 v[48:63], v[160:163], v[140:143], v[48:63]
	ds_read_b64_tr_b16 v[160:161], v0 offset:28672
	ds_read_b64_tr_b16 v[162:163], v0 offset:29184
	v_exp_f32_e32 v112, v114
	v_mfma_f32_32x32x16_bf16 v[48:63], v[10:13], v[136:139], v[48:63]
	ds_read_b64_tr_b16 v[10:11], v0 offset:29696
	ds_read_b64_tr_b16 v[12:13], v0 offset:30208
	v_exp_f32_e32 v98, v98
	v_mfma_f32_32x32x16_bf16 v[48:63], v[6:9], v[132:135], v[48:63]
	ds_read_b64_tr_b16 v[6:7], v0 offset:30720
	ds_read_b64_tr_b16 v[8:9], v0 offset:31232
	v_exp_f32_e32 v113, v115
	v_mfma_f32_32x32x16_bf16 v[48:63], v[2:5], v[180:183], v[48:63]
	ds_read_b64_tr_b16 v[2:3], v0 offset:31744
	ds_read_b64_tr_b16 v[4:5], v0 offset:32256
	v_exp_f32_e32 v0, v99
	s_waitcnt lgkmcnt(14)
	v_mfma_f32_32x32x16_bf16 v[32:47], v[128:131], v[140:143], v[32:47]
	v_exp_f32_e32 v99, v116
	v_exp_f32_e32 v100, v100
	v_exp_f32_e32 v114, v117
	s_waitcnt lgkmcnt(12)
	v_mfma_f32_32x32x16_bf16 v[32:47], v[172:175], v[136:139], v[32:47]
	v_exp_f32_e32 v101, v101
	v_exp_f32_e32 v115, v118
	v_exp_f32_e32 v102, v102
	s_waitcnt lgkmcnt(10)
	v_mfma_f32_32x32x16_bf16 v[32:47], v[168:171], v[132:135], v[32:47]
	v_exp_f32_e32 v116, v119
	v_exp_f32_e32 v103, v103
	v_exp_f32_e32 v117, v120
	s_waitcnt lgkmcnt(8)
	v_mfma_f32_32x32x16_bf16 v[32:47], v[164:167], v[180:183], v[32:47]
	v_exp_f32_e32 v104, v104
	v_exp_f32_e32 v118, v121
	v_exp_f32_e32 v105, v105
	s_waitcnt lgkmcnt(6)
	v_mfma_f32_32x32x16_bf16 v[16:31], v[160:163], v[140:143], v[16:31]
	v_exp_f32_e32 v119, v122
	v_exp_f32_e32 v106, v106
	v_exp_f32_e32 v120, v123
	s_waitcnt lgkmcnt(4)
	v_mfma_f32_32x32x16_bf16 v[16:31], v[10:13], v[136:139], v[16:31]
	v_exp_f32_e32 v10, v107
	v_exp_f32_e32 v11, v124
	v_exp_f32_e32 v12, v108
	s_waitcnt lgkmcnt(2)
	v_mfma_f32_32x32x16_bf16 v[16:31], v[6:9], v[132:135], v[16:31]
	v_exp_f32_e32 v6, v125
	v_exp_f32_e32 v7, v109
	v_exp_f32_e32 v8, v126
	s_waitcnt lgkmcnt(0)
	v_mfma_f32_32x32x16_bf16 v[16:31], v[2:5], v[180:183], v[16:31]
	v_mov_b64_e32 v[2:3], s[60:61]
	v_mov_b64_e32 v[4:5], s[62:63]
	v_exp_f32_e32 v107, v110
	s_nop 0
	v_mfma_f32_32x32x16_bf16 v[80:95], v[2:5], v[140:143], v[80:95]
	v_exp_f32_e32 v108, v127
	v_exp_f32_e32 v109, v111
	v_cvt_pk_bf16_f32 v140, v14, v96
	v_cvt_pk_bf16_f32 v143, v115, v116
	v_mfma_f32_32x32x16_bf16 v[80:95], v[2:5], v[136:139], v[80:95]
	v_cvt_pk_bf16_f32 v128, v104, v105
	v_cvt_pk_bf16_f32 v141, v112, v113
	v_cvt_pk_bf16_f32 v136, v117, v118
	v_mfma_f32_32x32x16_bf16 v[80:95], v[2:5], v[132:135], v[80:95]
	v_cvt_pk_bf16_f32 v137, v119, v120
	v_cvt_pk_bf16_f32 v129, v106, v10
	v_cvt_pk_bf16_f32 v132, v15, v97
	v_cvt_pk_bf16_f32 v130, v12, v7
	v_cvt_pk_bf16_f32 v138, v11, v6
	v_cvt_pk_bf16_f32 v133, v98, v0
	v_cvt_pk_bf16_f32 v142, v99, v114
	v_cvt_pk_bf16_f32 v134, v100, v101
	v_cvt_pk_bf16_f32 v135, v102, v103
	v_cvt_pk_bf16_f32 v139, v8, v108
	v_cvt_pk_bf16_f32 v131, v107, v109
	v_mfma_f32_32x32x16_bf16 v[80:95], v[2:5], v[180:183], v[80:95]
	s_add_i32 s28, s28, 1
	s_add_i32 s13, s13, 1
	s_add_i32 s19, s19, 0x8000
	s_cmpk_eq_i32 s13, 0x45
	s_cbranch_scc1 .LBB0_464

.Lf_462:
	s_and_b32 s17, s19, 0x18000
	v_add_u32_e32 v0, s17, v227
	v_add_u32_e32 v2, v0, v228
	ds_read_b128 v[96:99], v2
	ds_read_b128 v[100:103], v2 offset:4096
	v_add_u32_e32 v2, v0, v226
	ds_read_b128 v[180:183], v2
	ds_read_b128 v[230:233], v2 offset:4096
	v_add_u32_e32 v2, v0, v225
	v_add_u32_e32 v0, v0, v224
	s_min_u32 s16, s28, 1
	ds_read_b128 v[234:237], v2
	ds_read_b128 v[238:241], v2 offset:4096
	ds_read_b128 v[242:245], v0
	ds_read_b128 v[246:249], v0 offset:4096
	s_lshl_b32 s16, s16, 15
	s_sub_i32 s16, s19, s16
	s_and_b32 s16, s16, 0x18000
	v_add_u32_e32 v0, s16, v195
	s_setprio 1
	s_waitcnt lgkmcnt(6)
	v_mfma_f32_32x32x16_bf16 v[112:127], v[96:99], v[156:159], 0
	v_mfma_f32_32x32x16_bf16 v[96:111], v[100:103], v[156:159], 0
	s_waitcnt lgkmcnt(4)
	v_mfma_f32_32x32x16_bf16 v[112:127], v[180:183], v[152:155], v[112:127]
	v_mfma_f32_32x32x16_bf16 v[96:111], v[230:233], v[152:155], v[96:111]
	s_waitcnt lgkmcnt(2)
	v_mfma_f32_32x32x16_bf16 v[112:127], v[234:237], v[148:151], v[112:127]
	v_mfma_f32_32x32x16_bf16 v[96:111], v[238:241], v[148:151], v[96:111]
	s_waitcnt lgkmcnt(0)
	v_mfma_f32_32x32x16_bf16 v[112:127], v[242:245], v[144:147], v[112:127]
	v_mfma_f32_32x32x16_bf16 v[96:111], v[246:249], v[144:147], v[96:111]
	ds_read_b64_tr_b16 v[176:177], v0 offset:16384
	ds_read_b64_tr_b16 v[178:179], v0 offset:16896
	ds_read_b64_tr_b16 v[172:173], v0 offset:17408
	ds_read_b64_tr_b16 v[174:175], v0 offset:17920
	ds_read_b64_tr_b16 v[168:169], v0 offset:18432
	ds_read_b64_tr_b16 v[170:171], v0 offset:18944
	ds_read_b64_tr_b16 v[164:165], v0 offset:19456
	ds_read_b64_tr_b16 v[166:167], v0 offset:19968
	ds_read_b64_tr_b16 v[160:161], v0 offset:20480
	ds_read_b64_tr_b16 v[162:163], v0 offset:20992
	ds_read_b64_tr_b16 v[10:11], v0 offset:21504
	ds_read_b64_tr_b16 v[12:13], v0 offset:22016
	ds_read_b64_tr_b16 v[6:7], v0 offset:22528
	ds_read_b64_tr_b16 v[8:9], v0 offset:23040
	ds_read_b64_tr_b16 v[2:3], v0 offset:23552
	ds_read_b64_tr_b16 v[4:5], v0 offset:24064
	s_setprio 0
	v_max3_f32 v14, v112, v113, v114
	v_max3_f32 v15, v115, v116, v117
	v_max3_f32 v180, v118, v119, v120
	v_max3_f32 v181, v121, v122, v123
	v_max3_f32 v182, v124, v125, v126
	v_max3_f32 v183, v96, v97, v98
	v_max3_f32 v218, v99, v100, v101
	v_max3_f32 v219, v102, v103, v104
	s_nop 0
	v_max3_f32 v14, v14, v15, v180
	v_max3_f32 v220, v105, v106, v107
	v_max3_f32 v15, v181, v182, v127
	v_max3_f32 v221, v108, v109, v110
	s_xor_b64 s[30:31], s[4:5], -1
	v_max3_f32 v180, v183, v218, v219
	v_max3_f32 v181, v220, v221, v111
	s_nop 0
	v_max3_f32 v14, v14, v15, v180
	v_max_f32_e32 v14, v14, v181
	v_mov_b32_e32 v15, v14
	s_nop 1
	v_permlane32_swap_b32_e32 v15, v14
	v_max_f32_e32 v14, v14, v15
	v_cmp_lt_f32_e32 vcc, 0x42800000, v14
	s_waitcnt lgkmcnt(0)
	s_cbranch_vccz .Lf_459
	s_branch .Lf_to463
